# early prep_late group chosen by vb bit 5 (odd virtual XCDs) instead of bit 7
# baseline (speedup 1.0000x reference)
.LBB0_83:
	v_writelane_b32 v250, s20, 2
	v_writelane_b32 v250, s17, 3
	v_writelane_b32 v250, s42, 4
	s_nop 1
	v_writelane_b32 v250, s43, 5
	v_writelane_b32 v250, s40, 6
	s_nop 1
	v_writelane_b32 v250, s41, 7
	s_or_b64 exec, exec, s[6:7]
	s_bitcmp1_b32 s86, 5
	s_cbranch_scc0 .Lpl_skip_early
	s_mov_b32 s100, 1
	s_branch .Lpl_entry

.LBB0_294:
	s_and_b64 vcc, exec, s[6:7]
	s_cbranch_vccz .LBB0_337
	s_cmp_lt_i32 s86, 20
	s_cbranch_scc1 .LBB0_337
	s_bitcmp1_b32 s86, 5
	s_cbranch_scc1 .LBB0_337
